# static s_setprio 1 for blocks 0..255 (the ones that run the serial scans; their co-resident blocks 256..511 only poll the grid barrier in those phases)
# speedup vs baseline: 1.0104x; 1.0104x over previous
_Z8mega_fwd1P:
	s_cmpk_ge_u32 s2, 0x100
	s_cbranch_scc1 .Lprio_done
	s_setprio 1
.Lprio_done:
	s_load_dword s3, s[0:1], 0x128
	s_mov_b64 s[84:85], s[0:1]
	s_add_u32 s86, s84, 0x128
	v_and_b32_e32 v119, 0x3ff, v0
	s_addc_u32 s87, s85, 0
	s_mov_b64 s[8:9], s[0:1]
	v_mov_b32_e32 v2, v119
	s_mov_b32 s1, s2
	s_cmpk_gt_i32 s1, 0xbf
	s_movk_i32 s0, 0x3ff
	s_cbranch_scc1 .LBB0_7
	s_load_dwordx2 s[4:5], s[8:9], 0x120
	s_load_dwordx2 s[6:7], s[8:9], 0x8
	s_load_dwordx2 s[12:13], s[8:9], 0x18
	s_load_dwordx2 s[14:15], s[8:9], 0x28
	v_ashrrev_i32_e32 v1, 6, v2
	v_and_b32_e32 v12, 63, v2
	v_lshlrev_b32_e32 v3, 2, v1
	s_waitcnt lgkmcnt(0)
	s_add_u32 s10, s4, 0x100000
	s_movk_i32 s4, 0x80
	s_addc_u32 s11, s5, 0
	v_lshlrev_b32_e32 v4, 8, v1
	v_lshlrev_b32_e32 v8, 3, v2
	v_cmp_gt_i32_e64 s[4:5], s4, v2
	v_lshlrev_b32_e32 v2, 3, v12
	s_movk_i32 s16, 0x3000
	v_add3_u32 v13, 0, v3, v2
	v_add3_u32 v14, 0, v2, v3
	v_mad_i64_i32 v[2:3], s[16:17], v4, s16, 0
	v_ashrrev_i32_e32 v5, 31, v4
	v_lshl_or_b32 v2, v12, 2, v2
	v_lshl_add_u64 v[2:3], s[14:15], 0, v[2:3]
	s_mov_b64 s[14:15], 0x9000
	v_lshlrev_b64 v[6:7], 2, v[4:5]
	v_lshl_add_u64 v[2:3], v[2:3], 0, s[14:15]
	v_lshl_add_u64 v[4:5], s[12:13], 0, v[6:7]
	v_lshl_add_u64 v[6:7], s[6:7], 0, v[6:7]
	s_movk_i32 s18, 0xa000
	s_movk_i32 s19, 0xd000
	s_mov_b64 s[12:13], 0xc000
	v_add_u32_e32 v15, 0, v8
	s_movk_i32 s20, 0xc00
	s_branch .LBB0_3
